# diff unit epilogue: z / sub-norm gain loads hoisted (counted vmcnt); fox QK block: regular k-steps first, decay-bias k-step last
# speedup vs baseline: 1.0182x; 1.0044x over previous
.LBB0_473:
	s_bitcmp1_b32 s99, 0
	s_cselect_b32 s40, 0x5500, 0
	s_add_i32 s40, s40, 0
	v_add_u32_e32 v115, s40, v164
	v_add_u32_e32 v169, v115, v150
	ds_read_b128 v[106:109], v169
	ds_read_b128 v[110:113], v169 offset:32
	ds_read_b128 v[116:119], v169 offset:4608
	ds_read_b128 v[120:123], v169 offset:4640
	ds_read_b128 v[124:127], v169 offset:64
	ds_read_b128 v[132:135], v169 offset:96
	ds_read_b128 v[128:131], v169 offset:4672
	ds_read_b128 v[170:173], v169 offset:4704
	v_mov_b32_e32 v248, s97
	ds_read_b32 v249, v248
	ds_read_b128 v[244:247], v115 offset:128
	ds_read_b128 v[136:139], v115 offset:4736
	v_cndmask_b32_e64 v140, 0, v114, s[46:47]
	v_mov_b32_e32 v143, v1
	s_setprio 1
	s_waitcnt lgkmcnt(10)
	v_mfma_f32_32x32x16_bf16 v[66:81], v[106:109], v[90:93], v[34:49]
	v_add3_u32 v106, s40, v161, v162
	v_add_u32_e32 v168, v106, v163
	s_waitcnt lgkmcnt(8)
	v_mfma_f32_32x32x16_bf16 v[50:65], v[116:119], v[90:93], v[34:49]
	v_mfma_f32_32x32x16_bf16 v[66:81], v[110:113], v[82:85], v[66:81]
	s_waitcnt lgkmcnt(7)
	v_mfma_f32_32x32x16_bf16 v[50:65], v[120:123], v[82:85], v[50:65]
	s_waitcnt lgkmcnt(6)
	v_mfma_f32_32x32x16_bf16 v[66:81], v[124:127], v[86:89], v[66:81]
	s_waitcnt lgkmcnt(4)
	v_mfma_f32_32x32x16_bf16 v[50:65], v[128:131], v[86:89], v[50:65]
	s_waitcnt lgkmcnt(2)
	v_sub_f32_e32 v250, v160, v249
	v_cvt_pk_bf16_f32 v251, v250, 0
	v_lshlrev_b32_e32 v251, 16, v251
	v_mfma_f32_32x32x16_bf16 v[66:81], v[132:135], v[94:97], v[66:81]
	v_sub_f32_e32 v250, v250, v251
	v_cvt_pk_bf16_f32 v252, v250, 0
	v_and_b32_e32 v253, 0xffff, v252
	v_lshlrev_b32_e32 v252, 16, v252
	v_mfma_f32_32x32x16_bf16 v[50:65], v[170:173], v[94:97], v[50:65]
	v_sub_f32_e32 v250, v250, v252
	v_cvt_pk_bf16_f32 v250, v250, 0
	v_or_b32_e32 v251, 0x3f80, v251
	v_lshl_or_b32 v250, v250, 16, v253
	v_cndmask_b32_e64 v142, 0, v250, s[46:47]
	v_cndmask_b32_e64 v141, 0, v251, s[46:47]
	ds_read_b64_tr_b16 v[124:125], v168 offset:9216
	ds_read_b64_tr_b16 v[126:127], v168 offset:10752
	ds_read_b64_tr_b16 v[108:109], v168 offset:10816
	ds_read_b64_tr_b16 v[106:107], v168 offset:9280
	ds_read_b64_tr_b16 v[128:129], v168 offset:12288
	ds_read_b64_tr_b16 v[130:131], v168 offset:13824
	ds_read_b64_tr_b16 v[112:113], v168 offset:13888
	ds_read_b64_tr_b16 v[110:111], v168 offset:12352
	s_waitcnt lgkmcnt(9)
	v_mfma_f32_32x32x16_bf16 v[66:81], v[244:247], v[140:143], v[66:81]
	s_waitcnt lgkmcnt(8)
	s_setprio 0
	ds_read_b64_tr_b16 v[132:133], v168 offset:15360
	ds_read_b64_tr_b16 v[134:135], v168 offset:16896
	ds_read_b64_tr_b16 v[118:119], v168 offset:16960
	ds_read_b64_tr_b16 v[116:117], v168 offset:15424
	v_mfma_f32_32x32x16_bf16 v[50:65], v[136:139], v[140:143], v[50:65]
	ds_read_b64_tr_b16 v[136:137], v168 offset:18432
	ds_read_b64_tr_b16 v[138:139], v168 offset:19968
	ds_read_b64_tr_b16 v[122:123], v168 offset:20032
	ds_read_b64_tr_b16 v[120:121], v168 offset:18496
	s_cmp_lg_u32 s99, 0
	s_cselect_b64 s[40:41], -1, 0
	s_cmp_lt_i32 s99, s95
	s_cselect_b64 s[48:49], -1, 0
	s_and_b64 s[50:51], s[40:41], s[48:49]
	s_and_b64 vcc, exec, s[50:51]
	s_cbranch_vccnz .LBB0_475
	v_add_u32_e32 v141, s98, v151
	v_cmp_gt_i32_e32 vcc, 48, v141
	v_cmp_gt_i32_e64 s[48:49], v141, v146
	s_or_b64 vcc, vcc, s[48:49]
	v_add_u32_e32 v142, 32, v141
	v_cndmask_b32_e32 v66, v66, v223, vcc
	v_cmp_gt_i32_e32 vcc, 16, v141
	v_cmp_gt_i32_e64 s[48:49], v142, v146
	s_or_b64 vcc, vcc, s[48:49]
	v_add_u32_e32 v142, 1, v141
	v_cndmask_b32_e32 v50, v50, v223, vcc
	v_cmp_gt_i32_e32 vcc, 48, v142
	v_cmp_ge_i32_e64 s[48:49], v141, v146
	s_or_b64 vcc, s[48:49], vcc
	v_cndmask_b32_e32 v67, v67, v223, vcc
	v_cmp_gt_i32_e32 vcc, 16, v142
	v_add_u32_e32 v142, 33, v141
	v_cmp_gt_i32_e64 s[48:49], v142, v146
	s_or_b64 vcc, vcc, s[48:49]
	v_add_u32_e32 v142, 2, v141
	v_cndmask_b32_e32 v51, v51, v223, vcc
	v_cmp_gt_i32_e32 vcc, 48, v142
	v_cmp_gt_i32_e64 s[48:49], v142, v146
	s_or_b64 vcc, vcc, s[48:49]
	v_cndmask_b32_e32 v68, v68, v223, vcc
	v_cmp_gt_i32_e32 vcc, 16, v142
	v_add_u32_e32 v142, 34, v141
	v_cmp_gt_i32_e64 s[48:49], v142, v146
	s_or_b64 vcc, vcc, s[48:49]
	v_add_u32_e32 v142, 3, v141
	v_cndmask_b32_e32 v52, v52, v223, vcc
	v_cmp_gt_i32_e32 vcc, 48, v142
	v_cmp_gt_i32_e64 s[48:49], v142, v146
	s_or_b64 vcc, vcc, s[48:49]
	v_cndmask_b32_e32 v69, v69, v223, vcc
	v_cmp_gt_i32_e32 vcc, 16, v142
	v_add_u32_e32 v142, 35, v141
	v_cmp_gt_i32_e64 s[48:49], v142, v146
	s_or_b64 vcc, vcc, s[48:49]
	v_add_u32_e32 v142, 8, v141
	v_cndmask_b32_e32 v53, v53, v223, vcc
	v_cmp_gt_i32_e32 vcc, 48, v142
	v_cmp_gt_i32_e64 s[48:49], v142, v146
	s_or_b64 vcc, vcc, s[48:49]
	v_cndmask_b32_e32 v70, v70, v223, vcc
	v_cmp_gt_i32_e32 vcc, 16, v142
	v_add_u32_e32 v142, 40, v141
	v_cmp_gt_i32_e64 s[48:49], v142, v146
	s_or_b64 vcc, vcc, s[48:49]
	v_add_u32_e32 v142, 9, v141
	v_cndmask_b32_e32 v54, v54, v223, vcc
	v_cmp_gt_i32_e32 vcc, 48, v142
	v_cmp_gt_i32_e64 s[48:49], v142, v146
	s_or_b64 vcc, vcc, s[48:49]
	v_cndmask_b32_e32 v71, v71, v223, vcc
	v_cmp_gt_i32_e32 vcc, 16, v142
	v_add_u32_e32 v142, 41, v141
	v_cmp_gt_i32_e64 s[48:49], v142, v146
	s_or_b64 vcc, vcc, s[48:49]
	v_add_u32_e32 v142, 10, v141
	v_cndmask_b32_e32 v55, v55, v223, vcc
	v_cmp_gt_i32_e32 vcc, 48, v142
	v_cmp_gt_i32_e64 s[48:49], v142, v146
	s_or_b64 vcc, vcc, s[48:49]
	v_cndmask_b32_e32 v72, v72, v223, vcc
	v_cmp_gt_i32_e32 vcc, 16, v142
	v_add_u32_e32 v142, 42, v141
	v_cmp_gt_i32_e64 s[48:49], v142, v146
	s_or_b64 vcc, vcc, s[48:49]
	v_add_u32_e32 v142, 11, v141
	v_cndmask_b32_e32 v56, v56, v223, vcc
	v_cmp_gt_i32_e32 vcc, 48, v142
	v_cmp_gt_i32_e64 s[48:49], v142, v146
	s_or_b64 vcc, vcc, s[48:49]
	v_cndmask_b32_e32 v73, v73, v223, vcc
	v_cmp_gt_i32_e32 vcc, 16, v142
	v_add_u32_e32 v142, 43, v141
	v_cmp_gt_i32_e64 s[48:49], v142, v146
	s_or_b64 vcc, vcc, s[48:49]
	v_add_u32_e32 v142, 16, v141
	v_cndmask_b32_e32 v57, v57, v223, vcc
	v_cmp_gt_i32_e32 vcc, 48, v142
	v_cmp_gt_i32_e64 s[48:49], v142, v146
	s_or_b64 vcc, vcc, s[48:49]
	s_cmp_lt_i32 s99, 0
	v_add_u32_e32 v142, 48, v141
	v_cndmask_b32_e32 v74, v74, v223, vcc
	s_cselect_b64 s[40:41], -1, 0
	v_cmp_gt_i32_e32 vcc, v142, v146
	s_or_b64 vcc, s[40:41], vcc
	v_add_u32_e32 v142, 17, v141
	v_cndmask_b32_e32 v58, v58, v223, vcc
	v_cmp_gt_i32_e32 vcc, 48, v142
	v_cmp_gt_i32_e64 s[48:49], v142, v146
	s_or_b64 vcc, vcc, s[48:49]
	v_add_u32_e32 v142, 49, v141
	v_cndmask_b32_e32 v75, v75, v223, vcc
	v_cmp_gt_i32_e32 vcc, v142, v146
	s_or_b64 vcc, s[40:41], vcc
	v_add_u32_e32 v142, 18, v141
	v_cndmask_b32_e32 v59, v59, v223, vcc
	v_cmp_gt_i32_e32 vcc, 48, v142
	v_cmp_gt_i32_e64 s[48:49], v142, v146
	s_or_b64 vcc, vcc, s[48:49]
	v_add_u32_e32 v142, 50, v141
	v_cndmask_b32_e32 v76, v76, v223, vcc
	v_cmp_gt_i32_e32 vcc, v142, v146
	s_or_b64 vcc, s[40:41], vcc
	v_add_u32_e32 v142, 19, v141
	v_cndmask_b32_e32 v60, v60, v223, vcc
	v_cmp_gt_i32_e32 vcc, 48, v142
	v_cmp_gt_i32_e64 s[48:49], v142, v146
	s_or_b64 vcc, vcc, s[48:49]
	v_add_u32_e32 v142, 51, v141
	v_cndmask_b32_e32 v77, v77, v223, vcc
	v_cmp_gt_i32_e32 vcc, v142, v146
	s_or_b64 vcc, s[40:41], vcc
	v_add_u32_e32 v142, 24, v141
	v_cndmask_b32_e32 v61, v61, v223, vcc
	v_cmp_gt_i32_e32 vcc, 48, v142
	v_cmp_gt_i32_e64 s[48:49], v142, v146
	s_or_b64 vcc, vcc, s[48:49]
	v_add_u32_e32 v142, 56, v141
	v_cndmask_b32_e32 v78, v78, v223, vcc
	v_cmp_gt_i32_e32 vcc, v142, v146
	s_or_b64 vcc, s[40:41], vcc
	v_add_u32_e32 v142, 25, v141
	v_cndmask_b32_e32 v62, v62, v223, vcc
	v_cmp_gt_i32_e32 vcc, 48, v142
	v_cmp_gt_i32_e64 s[48:49], v142, v146
	s_or_b64 vcc, vcc, s[48:49]
	v_add_u32_e32 v142, 57, v141
	v_cndmask_b32_e32 v79, v79, v223, vcc
	v_cmp_gt_i32_e32 vcc, v142, v146
	s_or_b64 vcc, s[40:41], vcc
	v_add_u32_e32 v142, 26, v141
	v_cndmask_b32_e32 v63, v63, v223, vcc
	v_cmp_gt_i32_e32 vcc, 48, v142
	v_cmp_gt_i32_e64 s[48:49], v142, v146
	s_or_b64 vcc, vcc, s[48:49]
	v_add_u32_e32 v142, 58, v141
	v_cndmask_b32_e32 v80, v80, v223, vcc
	v_cmp_gt_i32_e32 vcc, v142, v146
	s_or_b64 vcc, s[40:41], vcc
	v_add_u32_e32 v142, 27, v141
	v_cndmask_b32_e32 v64, v64, v223, vcc
	v_cmp_gt_i32_e32 vcc, 48, v142
	v_cmp_gt_i32_e64 s[48:49], v142, v146
	s_or_b64 vcc, vcc, s[48:49]
	v_add_u32_e32 v141, 59, v141
	v_cndmask_b32_e32 v81, v81, v223, vcc
	v_cmp_gt_i32_e32 vcc, v141, v146
	s_or_b64 vcc, s[40:41], vcc
	s_nop 0
	v_cndmask_b32_e32 v65, v65, v223, vcc

; #define LAS __attribute__((address_space(3)))
; __device__ __forceinline__ float swap32_sum(float m) { auto rr = __builtin_amdgcn_permlane32_swap(__float_as_uint(m), __float_as_uint(m), false, false); return __uint_as_float(rr[0]) + __uint_as_float(rr[1]); }
; template <bool DIFF>
; __device__ __forceinline__ void attn_unit(const AttnP& A, int b, int h, int qi, ldsp lds) {
;     ...
;         LAS float* xch = (LAS float*)lds;
;         if (comp == 1) {
;             const float f = inv * A.lam;
; #pragma unroll
;             for (int t = 0; t < NTD; ++t)
; #pragma unroll
;                 for (int r = 0; r < 16; ++r) xch[(t * 16 + r) * 256 + wq * 64 + lane] = o[t][r] * f;
;         }
;         __syncthreads();
;         if (comp == 0) {
;             float ss = 0.f;
; #pragma unroll
;             for (int t = 0; t < NTD; ++t)
; #pragma unroll
;                 for (int r = 0; r < 16; ++r) { const float v = o[t][r] * inv - xch[(t * 16 + r) * 256 + wq * 64 + lane]; o[t][r] = v; ss += v * v; }
;             ss = swap32_sum(ss);
.LBB0_521:
	s_cmpk_gt_u32 s64, 0xff
	s_waitcnt lgkmcnt(0)
	s_barrier
	s_cbranch_scc1 .LBB0_438
	s_cmp_lt_u32 s51, 4
	s_cselect_b64 s[0:1], -1, 0
	s_and_b32 s22, s64, 0xc0
	s_lshl_b32 s22, s22, 2
	s_add_i32 s22, s22, 0
	v_lshl_add_u32 v82, v66, 2, s22
	ds_read2st64_b32 v[66:67], v82 offset1:4
	v_and_b32_e32 v68, -16, v192
	v_cmp_eq_u32_e32 vcc, 48, v68
	ds_read2st64_b32 v[68:69], v82 offset0:8 offset1:12
	s_and_b64 s[0:1], s[0:1], vcc
	s_waitcnt lgkmcnt(1)
	v_pk_fma_f32 v[78:79], v[50:51], v[0:1], v[66:67] op_sel_hi:[1,0,1] neg_lo:[0,0,1] neg_hi:[0,0,1]
	s_or_b64 s[16:17], s[16:17], s[0:1]
	v_mul_f32_e32 v50, v79, v79
	v_pk_fma_f32 v[50:51], v[78:79], v[78:79], v[50:51] op_sel_hi:[1,1,0]
	s_waitcnt lgkmcnt(0)
	v_pk_fma_f32 v[80:81], v[52:53], v[0:1], v[68:69] op_sel_hi:[1,0,1] neg_lo:[0,0,1] neg_hi:[0,0,1]
	ds_read2st64_b32 v[52:53], v82 offset0:16 offset1:20
	v_pk_fma_f32 v[50:51], v[80:81], v[80:81], v[50:51]
	v_mul_f32_e32 v66, v81, v81
	v_pk_add_f32 v[50:51], v[50:51], v[66:67] op_sel_hi:[1,0]
	ds_read2st64_b32 v[66:67], v82 offset0:24 offset1:28
	s_waitcnt lgkmcnt(1)
	v_pk_fma_f32 v[74:75], v[54:55], v[0:1], v[52:53] op_sel_hi:[1,0,1] neg_lo:[0,0,1] neg_hi:[0,0,1]
	s_waitcnt lgkmcnt(0)
	v_pk_fma_f32 v[72:73], v[56:57], v[0:1], v[66:67] op_sel_hi:[1,0,1] neg_lo:[0,0,1] neg_hi:[0,0,1]
	v_pk_fma_f32 v[50:51], v[74:75], v[74:75], v[50:51]
	v_mul_f32_e32 v52, v75, v75
	v_pk_add_f32 v[50:51], v[50:51], v[52:53] op_sel_hi:[1,0]
	ds_read2st64_b32 v[52:53], v82 offset0:32 offset1:36
	v_pk_fma_f32 v[50:51], v[72:73], v[72:73], v[50:51]
	v_mul_f32_e32 v54, v73, v73
	v_pk_add_f32 v[50:51], v[50:51], v[54:55] op_sel_hi:[1,0]
	ds_read2st64_b32 v[54:55], v82 offset0:40 offset1:44
	s_waitcnt lgkmcnt(1)
	v_pk_fma_f32 v[70:71], v[58:59], v[0:1], v[52:53] op_sel_hi:[1,0,1] neg_lo:[0,0,1] neg_hi:[0,0,1]
	s_waitcnt lgkmcnt(0)
	v_pk_fma_f32 v[68:69], v[60:61], v[0:1], v[54:55] op_sel_hi:[1,0,1] neg_lo:[0,0,1] neg_hi:[0,0,1]
	v_pk_fma_f32 v[50:51], v[70:71], v[70:71], v[50:51]
	v_mul_f32_e32 v52, v71, v71
	v_pk_add_f32 v[50:51], v[50:51], v[52:53] op_sel_hi:[1,0]
	ds_read2st64_b32 v[52:53], v82 offset0:48 offset1:52
	v_pk_fma_f32 v[50:51], v[68:69], v[68:69], v[50:51]
	v_mul_f32_e32 v54, v69, v69
	v_pk_add_f32 v[50:51], v[50:51], v[54:55] op_sel_hi:[1,0]
	ds_read2st64_b32 v[54:55], v82 offset0:56 offset1:60
	s_waitcnt lgkmcnt(1)
	v_pk_fma_f32 v[66:67], v[62:63], v[0:1], v[52:53] op_sel_hi:[1,0,1] neg_lo:[0,0,1] neg_hi:[0,0,1]
	s_waitcnt lgkmcnt(0)
	v_pk_fma_f32 v[64:65], v[64:65], v[0:1], v[54:55] op_sel_hi:[1,0,1] neg_lo:[0,0,1] neg_hi:[0,0,1]
	v_pk_fma_f32 v[50:51], v[66:67], v[66:67], v[50:51]
	v_mul_f32_e32 v52, v67, v67
	v_pk_add_f32 v[50:51], v[50:51], v[52:53] op_sel_hi:[1,0]
	ds_read2st64_b32 v[52:53], v82 offset0:64 offset1:68
	v_pk_fma_f32 v[50:51], v[64:65], v[64:65], v[50:51]
	v_mul_f32_e32 v54, v65, v65
	v_pk_add_f32 v[50:51], v[50:51], v[54:55] op_sel_hi:[1,0]
	ds_read2st64_b32 v[54:55], v82 offset0:72 offset1:76
	s_waitcnt lgkmcnt(1)
	v_pk_fma_f32 v[62:63], v[34:35], v[0:1], v[52:53] op_sel_hi:[1,0,1] neg_lo:[0,0,1] neg_hi:[0,0,1]
	s_waitcnt lgkmcnt(0)
	v_pk_fma_f32 v[60:61], v[36:37], v[0:1], v[54:55] op_sel_hi:[1,0,1] neg_lo:[0,0,1] neg_hi:[0,0,1]
	v_pk_fma_f32 v[34:35], v[62:63], v[62:63], v[50:51]
	v_mul_f32_e32 v50, v63, v63
	v_pk_add_f32 v[34:35], v[34:35], v[50:51] op_sel_hi:[1,0]
	ds_read2st64_b32 v[36:37], v82 offset0:80 offset1:84
	v_pk_fma_f32 v[34:35], v[60:61], v[60:61], v[34:35]
	v_mul_f32_e32 v50, v61, v61
	v_pk_add_f32 v[34:35], v[34:35], v[50:51] op_sel_hi:[1,0]
	ds_read2st64_b32 v[50:51], v82 offset0:88 offset1:92
	s_waitcnt lgkmcnt(1)
	v_pk_fma_f32 v[58:59], v[38:39], v[0:1], v[36:37] op_sel_hi:[1,0,1] neg_lo:[0,0,1] neg_hi:[0,0,1]
	s_waitcnt lgkmcnt(0)
	v_pk_fma_f32 v[56:57], v[40:41], v[0:1], v[50:51] op_sel_hi:[1,0,1] neg_lo:[0,0,1] neg_hi:[0,0,1]
	v_pk_fma_f32 v[34:35], v[58:59], v[58:59], v[34:35]
	v_mul_f32_e32 v36, v59, v59
	v_pk_add_f32 v[34:35], v[34:35], v[36:37] op_sel_hi:[1,0]
	ds_read2st64_b32 v[36:37], v82 offset0:96 offset1:100
	v_pk_fma_f32 v[34:35], v[56:57], v[56:57], v[34:35]
	v_mul_f32_e32 v38, v57, v57
	v_pk_add_f32 v[34:35], v[34:35], v[38:39] op_sel_hi:[1,0]
	ds_read2st64_b32 v[38:39], v82 offset0:104 offset1:108
	s_waitcnt lgkmcnt(1)
	v_pk_fma_f32 v[54:55], v[42:43], v[0:1], v[36:37] op_sel_hi:[1,0,1] neg_lo:[0,0,1] neg_hi:[0,0,1]
	s_waitcnt lgkmcnt(0)
	v_pk_fma_f32 v[52:53], v[44:45], v[0:1], v[38:39] op_sel_hi:[1,0,1] neg_lo:[0,0,1] neg_hi:[0,0,1]
	v_pk_fma_f32 v[34:35], v[54:55], v[54:55], v[34:35]
	v_mul_f32_e32 v36, v55, v55
	v_pk_add_f32 v[34:35], v[34:35], v[36:37] op_sel_hi:[1,0]
	ds_read2st64_b32 v[36:37], v82 offset0:112 offset1:116
	v_pk_fma_f32 v[34:35], v[52:53], v[52:53], v[34:35]
	v_mul_f32_e32 v38, v53, v53
	v_pk_add_f32 v[34:35], v[34:35], v[38:39] op_sel_hi:[1,0]
	ds_read2st64_b32 v[38:39], v82 offset0:120 offset1:124
	s_waitcnt lgkmcnt(1)
	v_pk_fma_f32 v[50:51], v[46:47], v[0:1], v[36:37] op_sel_hi:[1,0,1] neg_lo:[0,0,1] neg_hi:[0,0,1]
	s_waitcnt lgkmcnt(0)
	v_pk_fma_f32 v[46:47], v[48:49], v[0:1], v[38:39] op_sel_hi:[1,0,1] neg_lo:[0,0,1] neg_hi:[0,0,1]
	v_pk_fma_f32 v[34:35], v[50:51], v[50:51], v[34:35]
	v_mul_f32_e32 v36, v51, v51
	v_pk_add_f32 v[34:35], v[34:35], v[36:37] op_sel_hi:[1,0]
	ds_read2st64_b32 v[36:37], v82 offset0:128 offset1:132
	v_pk_fma_f32 v[34:35], v[46:47], v[46:47], v[34:35]
	v_mul_f32_e32 v38, v47, v47
	v_pk_add_f32 v[34:35], v[34:35], v[38:39] op_sel_hi:[1,0]
	ds_read2st64_b32 v[38:39], v82 offset0:136 offset1:140
	s_waitcnt lgkmcnt(1)
	v_pk_fma_f32 v[44:45], v[18:19], v[0:1], v[36:37] op_sel_hi:[1,0,1] neg_lo:[0,0,1] neg_hi:[0,0,1]
	s_waitcnt lgkmcnt(0)
; __device__ __forceinline__ float swap32_sum(float m) { auto rr = __builtin_amdgcn_permlane32_swap(__float_as_uint(m), __float_as_uint(m), false, false); return __uint_as_float(rr[0]) + __uint_as_float(rr[1]); }
; template <bool DIFF>
; __device__ __forceinline__ void attn_unit(const AttnP& A, int b, int h, int qi, ldsp lds) {
;     ...
;             for (int t = 0; t < NTD; ++t)
; #pragma unroll
;                 for (int r = 0; r < 16; ++r) { const float v = o[t][r] * inv - xch[(t * 16 + r) * 256 + wq * 64 + lane]; o[t][r] = v; ss += v * v; }
;             ss = swap32_sum(ss);
;             const float rn = rsqrtf(ss * (1.0f / 128.0f) + NORM_EPS) * A.one_m_li;
;             if (store_ok) {
	v_pk_fma_f32 v[42:43], v[20:21], v[0:1], v[38:39] op_sel_hi:[1,0,1] neg_lo:[0,0,1] neg_hi:[0,0,1]
	v_pk_fma_f32 v[18:19], v[44:45], v[44:45], v[34:35]
	v_mul_f32_e32 v34, v45, v45
	v_pk_add_f32 v[18:19], v[18:19], v[34:35] op_sel_hi:[1,0]
	ds_read2st64_b32 v[20:21], v82 offset0:144 offset1:148
	v_pk_fma_f32 v[18:19], v[42:43], v[42:43], v[18:19]
	v_mul_f32_e32 v34, v43, v43
	v_pk_add_f32 v[18:19], v[18:19], v[34:35] op_sel_hi:[1,0]
	ds_read2st64_b32 v[34:35], v82 offset0:152 offset1:156
	s_waitcnt lgkmcnt(1)
	v_pk_fma_f32 v[40:41], v[22:23], v[0:1], v[20:21] op_sel_hi:[1,0,1] neg_lo:[0,0,1] neg_hi:[0,0,1]
	s_waitcnt lgkmcnt(0)
	v_pk_fma_f32 v[38:39], v[24:25], v[0:1], v[34:35] op_sel_hi:[1,0,1] neg_lo:[0,0,1] neg_hi:[0,0,1]
	v_pk_fma_f32 v[18:19], v[40:41], v[40:41], v[18:19]
	v_mul_f32_e32 v20, v41, v41
	v_pk_add_f32 v[18:19], v[18:19], v[20:21] op_sel_hi:[1,0]
	ds_read2st64_b32 v[20:21], v82 offset0:160 offset1:164
	v_pk_fma_f32 v[18:19], v[38:39], v[38:39], v[18:19]
	v_mul_f32_e32 v22, v39, v39
	v_pk_add_f32 v[18:19], v[18:19], v[22:23] op_sel_hi:[1,0]
	ds_read2st64_b32 v[22:23], v82 offset0:168 offset1:172
	s_waitcnt lgkmcnt(1)
	v_pk_fma_f32 v[36:37], v[26:27], v[0:1], v[20:21] op_sel_hi:[1,0,1] neg_lo:[0,0,1] neg_hi:[0,0,1]
	s_waitcnt lgkmcnt(0)
	v_pk_fma_f32 v[34:35], v[28:29], v[0:1], v[22:23] op_sel_hi:[1,0,1] neg_lo:[0,0,1] neg_hi:[0,0,1]
	v_pk_fma_f32 v[18:19], v[36:37], v[36:37], v[18:19]
	v_mul_f32_e32 v20, v37, v37
	v_pk_add_f32 v[18:19], v[18:19], v[20:21] op_sel_hi:[1,0]
	ds_read2st64_b32 v[20:21], v82 offset0:176 offset1:180
	v_pk_fma_f32 v[18:19], v[34:35], v[34:35], v[18:19]
	v_mul_f32_e32 v22, v35, v35
	v_pk_add_f32 v[18:19], v[18:19], v[22:23] op_sel_hi:[1,0]
	ds_read2st64_b32 v[22:23], v82 offset0:184 offset1:188
	s_waitcnt lgkmcnt(1)
	v_pk_fma_f32 v[28:29], v[30:31], v[0:1], v[20:21] op_sel_hi:[1,0,1] neg_lo:[0,0,1] neg_hi:[0,0,1]
	s_waitcnt lgkmcnt(0)
	v_pk_fma_f32 v[26:27], v[32:33], v[0:1], v[22:23] op_sel_hi:[1,0,1] neg_lo:[0,0,1] neg_hi:[0,0,1]
	v_pk_fma_f32 v[18:19], v[28:29], v[28:29], v[18:19]
	v_mul_f32_e32 v20, v29, v29
	v_pk_add_f32 v[18:19], v[18:19], v[20:21] op_sel_hi:[1,0]
	ds_read2st64_b32 v[20:21], v82 offset0:192 offset1:196
	v_pk_fma_f32 v[18:19], v[26:27], v[26:27], v[18:19]
	v_mul_f32_e32 v22, v27, v27
	v_pk_add_f32 v[18:19], v[18:19], v[22:23] op_sel_hi:[1,0]
	ds_read2st64_b32 v[22:23], v82 offset0:200 offset1:204
	s_waitcnt lgkmcnt(1)
	v_pk_fma_f32 v[24:25], v[2:3], v[0:1], v[20:21] op_sel_hi:[1,0,1] neg_lo:[0,0,1] neg_hi:[0,0,1]
	s_waitcnt lgkmcnt(0)
	v_pk_fma_f32 v[22:23], v[4:5], v[0:1], v[22:23] op_sel_hi:[1,0,1] neg_lo:[0,0,1] neg_hi:[0,0,1]
	v_pk_fma_f32 v[2:3], v[24:25], v[24:25], v[18:19]
	v_mul_f32_e32 v18, v25, v25
	v_pk_add_f32 v[2:3], v[2:3], v[18:19] op_sel_hi:[1,0]
	ds_read2st64_b32 v[4:5], v82 offset0:208 offset1:212
	v_pk_fma_f32 v[2:3], v[22:23], v[22:23], v[2:3]
	v_mul_f32_e32 v18, v23, v23
	v_pk_add_f32 v[2:3], v[2:3], v[18:19] op_sel_hi:[1,0]
	ds_read2st64_b32 v[18:19], v82 offset0:216 offset1:220
	s_waitcnt lgkmcnt(1)
	v_pk_fma_f32 v[20:21], v[6:7], v[0:1], v[4:5] op_sel_hi:[1,0,1] neg_lo:[0,0,1] neg_hi:[0,0,1]
	s_waitcnt lgkmcnt(0)
	v_pk_fma_f32 v[18:19], v[8:9], v[0:1], v[18:19] op_sel_hi:[1,0,1] neg_lo:[0,0,1] neg_hi:[0,0,1]
	v_pk_fma_f32 v[2:3], v[20:21], v[20:21], v[2:3]
	v_mul_f32_e32 v4, v21, v21
	v_pk_add_f32 v[2:3], v[2:3], v[4:5] op_sel_hi:[1,0]
	ds_read2st64_b32 v[4:5], v82 offset0:224 offset1:228
	v_pk_fma_f32 v[2:3], v[18:19], v[18:19], v[2:3]
	v_mul_f32_e32 v6, v19, v19
	v_pk_add_f32 v[2:3], v[2:3], v[6:7] op_sel_hi:[1,0]
	ds_read2st64_b32 v[6:7], v82 offset0:232 offset1:236
	s_waitcnt lgkmcnt(1)
	v_pk_fma_f32 v[10:11], v[10:11], v[0:1], v[4:5] op_sel_hi:[1,0,1] neg_lo:[0,0,1] neg_hi:[0,0,1]
	s_waitcnt lgkmcnt(0)
	v_pk_fma_f32 v[8:9], v[12:13], v[0:1], v[6:7] op_sel_hi:[1,0,1] neg_lo:[0,0,1] neg_hi:[0,0,1]
	v_pk_fma_f32 v[2:3], v[10:11], v[10:11], v[2:3]
	v_mul_f32_e32 v4, v11, v11
	v_pk_add_f32 v[2:3], v[2:3], v[4:5] op_sel_hi:[1,0]
	ds_read2st64_b32 v[4:5], v82 offset0:240 offset1:244
	v_pk_fma_f32 v[2:3], v[8:9], v[8:9], v[2:3]
	v_mul_f32_e32 v6, v9, v9
	v_pk_add_f32 v[2:3], v[2:3], v[6:7] op_sel_hi:[1,0]
	ds_read2st64_b32 v[6:7], v82 offset0:248 offset1:252
	s_waitcnt lgkmcnt(1)
	v_pk_fma_f32 v[4:5], v[14:15], v[0:1], v[4:5] op_sel_hi:[1,0,1] neg_lo:[0,0,1] neg_hi:[0,0,1]
	s_nop 0
	v_pk_fma_f32 v[2:3], v[4:5], v[4:5], v[2:3]
	v_mul_f32_e32 v12, v5, v5
	v_pk_add_f32 v[12:13], v[2:3], v[12:13] op_sel_hi:[1,0]
	s_waitcnt lgkmcnt(0)
	v_pk_fma_f32 v[2:3], v[16:17], v[0:1], v[6:7] op_sel_hi:[1,0,1] neg_lo:[0,0,1] neg_hi:[0,0,1]
	s_nop 0
	v_pk_fma_f32 v[6:7], v[2:3], v[2:3], v[12:13]
	v_mul_f32_e32 v0, v3, v3
	v_pk_add_f32 v[6:7], v[6:7], v[0:1] op_sel_hi:[1,0]
	s_nop 0
	v_mov_b32_e32 v0, v6
	s_nop 1
	v_permlane32_swap_b32_e32 v6, v0
	s_and_saveexec_b64 s[0:1], s[16:17]
	s_cbranch_execz .LBB0_437
; __device__ __forceinline__ unsigned cvtpk(float lo, float hi) { f32x2 v = {lo, hi}; bf16x2_t b = __builtin_convertvector(v, bf16x2_t); return __builtin_bit_cast(unsigned, b); }
; __device__ __forceinline__ float bf_lo(unsigned u) { return __uint_as_float(u << 16); }
; __device__ __forceinline__ float bf_hi(unsigned u) { return __uint_as_float(u & 0xffff0000u); }
; template <bool DIFF>
; __device__ __forceinline__ void attn_unit(const AttnP& A, int b, int h, int qi, ldsp lds) {
;     ...
;             const float rn = rsqrtf(ss * (1.0f / 128.0f) + NORM_EPS) * A.one_m_li;
;             if (store_ok) {
; #pragma unroll
;                 for (int t = 0; t < NTD; ++t)
; #pragma unroll
;                     for (int g = 0; g < 4; ++g) {
;                         const int dv0 = 32 * t + 8 * g + 4 * hi;
;                         const u32x2 z = *(const u32x2*)(A.P + Rq * NP + zcol + dv0);
;                         const f32x4 sg = *(const f32x4*)(A.subg + h * 128 + dv0);
;                         u32x2 wv; wv.x = cvtpk(o[t][4 * g] * rn * sg[0] * bf_lo(z.x), o[t][4 * g + 1] * rn * sg[1] * bf_hi(z.x));
;                         wv.y = cvtpk(o[t][4 * g + 2] * rn * sg[2] * bf_lo(z.y), o[t][4 * g + 3] * rn * sg[3] * bf_hi(z.y));
;                         *(u32x2*)(mrow + mcol + dv0) = wv;
;                     }
	v_add_f32_e32 v0, v6, v0
	v_fmamk_f32 v0, v0, 0x3c000000, v202
	v_cmp_gt_f32_e32 vcc, s18, v0
	v_mul_f32_e32 v6, 0x4b800000, v0
	s_lshl_b32 s16, s50, 2
	v_cndmask_b32_e32 v0, v0, v6, vcc
	v_rsq_f32_e32 v0, v0
	v_lshl_add_u64 v[12:13], v[190:191], 0, s[34:35]
	s_add_u32 s16, s88, s16
	s_addc_u32 s17, s89, 0
	v_mul_f32_e32 v6, 0x45800000, v0
	v_cndmask_b32_e32 v0, v0, v6, vcc
	v_mul_f32_e32 v6, v224, v0
	v_lshlrev_b32_e32 v0, 1, v115
	v_lshl_add_u64 v[12:13], v[12:13], 0, v[0:1]
	v_lshlrev_b32_e32 v7, 2, v115
	global_load_dwordx2 v[116:117], v[12:13], off offset:3072
	global_load_dwordx4 v[148:151], v7, s[16:17]
	global_load_dwordx2 v[118:119], v[12:13], off offset:3088
	global_load_dwordx4 v[152:155], v7, s[16:17] offset:32
	global_load_dwordx2 v[124:125], v[12:13], off offset:3104
	global_load_dwordx4 v[156:159], v7, s[16:17] offset:64
	global_load_dwordx2 v[126:127], v[12:13], off offset:3120
	global_load_dwordx4 v[160:163], v7, s[16:17] offset:96
	global_load_dwordx2 v[128:129], v[12:13], off offset:3136
	global_load_dwordx4 v[168:171], v7, s[16:17] offset:128
	global_load_dwordx2 v[130:131], v[12:13], off offset:3152
	global_load_dwordx4 v[172:175], v7, s[16:17] offset:160
	global_load_dwordx2 v[132:133], v[12:13], off offset:3168
	global_load_dwordx4 v[176:179], v7, s[16:17] offset:192
	global_load_dwordx2 v[134:135], v[12:13], off offset:3184
	global_load_dwordx4 v[192:195], v7, s[16:17] offset:224
	global_load_dwordx2 v[136:137], v[12:13], off offset:3200
	global_load_dwordx4 v[196:199], v7, s[16:17] offset:256
	global_load_dwordx2 v[138:139], v[12:13], off offset:3216
	global_load_dwordx4 v[228:231], v7, s[16:17] offset:288
	global_load_dwordx2 v[140:141], v[12:13], off offset:3232
	global_load_dwordx4 v[232:235], v7, s[16:17] offset:320
	global_load_dwordx2 v[142:143], v[12:13], off offset:3248
	global_load_dwordx4 v[236:239], v7, s[16:17] offset:352
	global_load_dwordx2 v[144:145], v[12:13], off offset:3264
	global_load_dwordx4 v[240:243], v7, s[16:17] offset:384
	global_load_dwordx2 v[146:147], v[12:13], off offset:3280
	global_load_dwordx4 v[244:247], v7, s[16:17] offset:416
	global_load_dwordx2 v[164:165], v[12:13], off offset:3296
	global_load_dwordx4 v[248:251], v7, s[16:17] offset:448
	global_load_dwordx2 v[204:205], v[12:13], off offset:3312
	global_load_dwordx4 v[120:123], v7, s[16:17] offset:480
	s_nop 0
	v_pk_mul_f32 v[48:49], v[78:79], v[6:7] op_sel_hi:[1,0]
	v_lshl_add_u64 v[30:31], v[76:77], 0, s[34:35]
	v_pk_mul_f32 v[44:45], v[44:45], v[6:7] op_sel_hi:[1,0]
	v_pk_mul_f32 v[40:41], v[40:41], v[6:7] op_sel_hi:[1,0]
	v_pk_mul_f32 v[36:37], v[36:37], v[6:7] op_sel_hi:[1,0]
	v_pk_mul_f32 v[28:29], v[28:29], v[6:7] op_sel_hi:[1,0]
	v_pk_mul_f32 v[26:27], v[26:27], v[6:7] op_sel_hi:[1,0]
	v_pk_mul_f32 v[24:25], v[24:25], v[6:7] op_sel_hi:[1,0]
	v_pk_mul_f32 v[22:23], v[22:23], v[6:7] op_sel_hi:[1,0]
	v_pk_mul_f32 v[20:21], v[20:21], v[6:7] op_sel_hi:[1,0]
	v_pk_mul_f32 v[18:19], v[18:19], v[6:7] op_sel_hi:[1,0]
	v_pk_mul_f32 v[10:11], v[10:11], v[6:7] op_sel_hi:[1,0]
	v_pk_mul_f32 v[8:9], v[8:9], v[6:7] op_sel_hi:[1,0]
	v_pk_mul_f32 v[4:5], v[4:5], v[6:7] op_sel_hi:[1,0]
	v_pk_mul_f32 v[2:3], v[2:3], v[6:7] op_sel_hi:[1,0]
	s_waitcnt vmcnt(30)
	v_mov_b32_e32 v32, v116
	v_mov_b32_e32 v33, v117
	v_mov_b32_e32 v14, v148
	v_mov_b32_e32 v15, v149
	v_mov_b32_e32 v16, v150
	v_mov_b32_e32 v17, v151
	v_pk_mul_f32 v[14:15], v[48:49], v[14:15]
	v_lshlrev_b32_e32 v48, 16, v32
	v_and_b32_e32 v49, 0xffff0000, v32
	v_pk_mul_f32 v[14:15], v[14:15], v[48:49]
	v_pk_mul_f32 v[48:49], v[74:75], v[6:7] op_sel_hi:[1,0]
	v_cvt_pk_bf16_f32 v32, v14, v15
	v_pk_mul_f32 v[14:15], v[80:81], v[6:7] op_sel_hi:[1,0]
	s_nop 0
	v_pk_mul_f32 v[14:15], v[14:15], v[16:17]
	v_lshlrev_b32_e32 v16, 16, v33
	v_and_b32_e32 v17, 0xffff0000, v33
	v_pk_mul_f32 v[14:15], v[14:15], v[16:17]
	s_nop 0
	v_cvt_pk_bf16_f32 v33, v14, v15
	v_lshl_add_u64 v[14:15], v[30:31], 0, v[0:1]
	global_store_dwordx2 v[14:15], v[32:33], off
	s_nop 0
	s_nop 0
	s_nop 0
	s_waitcnt vmcnt(29)
	v_mov_b32_e32 v16, v118
	v_mov_b32_e32 v17, v119
	v_mov_b32_e32 v30, v152
	v_mov_b32_e32 v31, v153
	v_mov_b32_e32 v32, v154
	v_mov_b32_e32 v33, v155
	v_pk_mul_f32 v[30:31], v[48:49], v[30:31]
	v_lshlrev_b32_e32 v48, 16, v16
	v_and_b32_e32 v49, 0xffff0000, v16
	v_pk_mul_f32 v[30:31], v[30:31], v[48:49]
	v_pk_mul_f32 v[48:49], v[70:71], v[6:7] op_sel_hi:[1,0]
	v_cvt_pk_bf16_f32 v16, v30, v31
	v_pk_mul_f32 v[30:31], v[72:73], v[6:7] op_sel_hi:[1,0]
	s_nop 0
	v_pk_mul_f32 v[30:31], v[30:31], v[32:33]
	v_lshlrev_b32_e32 v32, 16, v17
	v_and_b32_e32 v33, 0xffff0000, v17
	v_pk_mul_f32 v[30:31], v[30:31], v[32:33]
	s_nop 0
	v_cvt_pk_bf16_f32 v17, v30, v31
	global_store_dwordx2 v[14:15], v[16:17], off offset:16
	s_nop 0
	s_nop 0
	s_nop 0
	s_waitcnt vmcnt(28)
	v_mov_b32_e32 v16, v124
	v_mov_b32_e32 v17, v125
	v_mov_b32_e32 v30, v156
	v_mov_b32_e32 v31, v157
	v_mov_b32_e32 v32, v158
	v_mov_b32_e32 v33, v159
	v_pk_mul_f32 v[30:31], v[48:49], v[30:31]
	v_lshlrev_b32_e32 v48, 16, v16
	v_and_b32_e32 v49, 0xffff0000, v16
	v_pk_mul_f32 v[30:31], v[30:31], v[48:49]
	v_pk_mul_f32 v[48:49], v[66:67], v[6:7] op_sel_hi:[1,0]
	v_cvt_pk_bf16_f32 v16, v30, v31
	v_pk_mul_f32 v[30:31], v[68:69], v[6:7] op_sel_hi:[1,0]
	s_nop 0
	v_pk_mul_f32 v[30:31], v[30:31], v[32:33]
	v_lshlrev_b32_e32 v32, 16, v17
	v_and_b32_e32 v33, 0xffff0000, v17
	v_pk_mul_f32 v[30:31], v[30:31], v[32:33]
	s_nop 0
	v_cvt_pk_bf16_f32 v17, v30, v31
	global_store_dwordx2 v[14:15], v[16:17], off offset:32
	s_nop 0
	s_nop 0
	s_nop 0
	s_waitcnt vmcnt(27)
; __device__ __forceinline__ unsigned cvtpk(float lo, float hi) { f32x2 v = {lo, hi}; bf16x2_t b = __builtin_convertvector(v, bf16x2_t); return __builtin_bit_cast(unsigned, b); }
; __device__ __forceinline__ float bf_lo(unsigned u) { return __uint_as_float(u << 16); }
; __device__ __forceinline__ float bf_hi(unsigned u) { return __uint_as_float(u & 0xffff0000u); }
; template <bool DIFF>
; __device__ __forceinline__ void attn_unit(const AttnP& A, int b, int h, int qi, ldsp lds) {
;     ...
;             if (store_ok) {
; #pragma unroll
;                 for (int t = 0; t < NTD; ++t)
; #pragma unroll
;                     for (int g = 0; g < 4; ++g) {
;                         const int dv0 = 32 * t + 8 * g + 4 * hi;
;                         const u32x2 z = *(const u32x2*)(A.P + Rq * NP + zcol + dv0);
;                         const f32x4 sg = *(const f32x4*)(A.subg + h * 128 + dv0);
;                         u32x2 wv; wv.x = cvtpk(o[t][4 * g] * rn * sg[0] * bf_lo(z.x), o[t][4 * g + 1] * rn * sg[1] * bf_hi(z.x));
;                         wv.y = cvtpk(o[t][4 * g + 2] * rn * sg[2] * bf_lo(z.y), o[t][4 * g + 3] * rn * sg[3] * bf_hi(z.y));
;                         *(u32x2*)(mrow + mcol + dv0) = wv;
;                     }
	v_mov_b32_e32 v16, v126
	v_mov_b32_e32 v17, v127
	v_mov_b32_e32 v30, v160
	v_mov_b32_e32 v31, v161
	v_mov_b32_e32 v32, v162
	v_mov_b32_e32 v33, v163
	v_pk_mul_f32 v[30:31], v[48:49], v[30:31]
	v_lshlrev_b32_e32 v48, 16, v16
	v_and_b32_e32 v49, 0xffff0000, v16
	v_pk_mul_f32 v[30:31], v[30:31], v[48:49]
	v_pk_mul_f32 v[48:49], v[62:63], v[6:7] op_sel_hi:[1,0]
	v_cvt_pk_bf16_f32 v16, v30, v31
	v_pk_mul_f32 v[30:31], v[64:65], v[6:7] op_sel_hi:[1,0]
	s_nop 0
	v_pk_mul_f32 v[30:31], v[30:31], v[32:33]
	v_lshlrev_b32_e32 v32, 16, v17
	v_and_b32_e32 v33, 0xffff0000, v17
	v_pk_mul_f32 v[30:31], v[30:31], v[32:33]
	s_nop 0
	v_cvt_pk_bf16_f32 v17, v30, v31
	global_store_dwordx2 v[14:15], v[16:17], off offset:48
	s_nop 0
	s_nop 0
	s_nop 0
	s_waitcnt vmcnt(26)
	v_mov_b32_e32 v16, v128
	v_mov_b32_e32 v17, v129
	v_mov_b32_e32 v30, v168
	v_mov_b32_e32 v31, v169
	v_mov_b32_e32 v32, v170
	v_mov_b32_e32 v33, v171
	v_pk_mul_f32 v[30:31], v[48:49], v[30:31]
	v_lshlrev_b32_e32 v48, 16, v16
	v_and_b32_e32 v49, 0xffff0000, v16
	v_pk_mul_f32 v[30:31], v[30:31], v[48:49]
	v_pk_mul_f32 v[48:49], v[58:59], v[6:7] op_sel_hi:[1,0]
	v_cvt_pk_bf16_f32 v16, v30, v31
	v_pk_mul_f32 v[30:31], v[60:61], v[6:7] op_sel_hi:[1,0]
	s_nop 0
	v_pk_mul_f32 v[30:31], v[30:31], v[32:33]
	v_lshlrev_b32_e32 v32, 16, v17
	v_and_b32_e32 v33, 0xffff0000, v17
	v_pk_mul_f32 v[30:31], v[30:31], v[32:33]
	s_nop 0
	v_cvt_pk_bf16_f32 v17, v30, v31
	global_store_dwordx2 v[14:15], v[16:17], off offset:64
	s_nop 0
	s_nop 0
	s_nop 0
	s_waitcnt vmcnt(25)
	v_mov_b32_e32 v16, v130
	v_mov_b32_e32 v17, v131
	v_mov_b32_e32 v30, v172
	v_mov_b32_e32 v31, v173
	v_mov_b32_e32 v32, v174
	v_mov_b32_e32 v33, v175
	v_pk_mul_f32 v[30:31], v[48:49], v[30:31]
	v_lshlrev_b32_e32 v48, 16, v16
	v_and_b32_e32 v49, 0xffff0000, v16
	v_pk_mul_f32 v[30:31], v[30:31], v[48:49]
	v_pk_mul_f32 v[48:49], v[54:55], v[6:7] op_sel_hi:[1,0]
	v_cvt_pk_bf16_f32 v16, v30, v31
	v_pk_mul_f32 v[30:31], v[56:57], v[6:7] op_sel_hi:[1,0]
	s_nop 0
	v_pk_mul_f32 v[30:31], v[30:31], v[32:33]
	v_lshlrev_b32_e32 v32, 16, v17
	v_and_b32_e32 v33, 0xffff0000, v17
	v_pk_mul_f32 v[30:31], v[30:31], v[32:33]
	s_nop 0
	v_cvt_pk_bf16_f32 v17, v30, v31
	global_store_dwordx2 v[14:15], v[16:17], off offset:80
	s_nop 0
	s_nop 0
	s_nop 0
	s_waitcnt vmcnt(24)
	v_mov_b32_e32 v16, v132
	v_mov_b32_e32 v17, v133
	v_mov_b32_e32 v30, v176
	v_mov_b32_e32 v31, v177
	v_mov_b32_e32 v32, v178
	v_mov_b32_e32 v33, v179
	v_pk_mul_f32 v[30:31], v[48:49], v[30:31]
	v_lshlrev_b32_e32 v48, 16, v16
	v_and_b32_e32 v49, 0xffff0000, v16
	v_pk_mul_f32 v[30:31], v[30:31], v[48:49]
	v_pk_mul_f32 v[48:49], v[50:51], v[6:7] op_sel_hi:[1,0]
	v_cvt_pk_bf16_f32 v16, v30, v31
	v_pk_mul_f32 v[30:31], v[52:53], v[6:7] op_sel_hi:[1,0]
	s_nop 0
	v_pk_mul_f32 v[30:31], v[30:31], v[32:33]
	v_lshlrev_b32_e32 v32, 16, v17
	v_and_b32_e32 v33, 0xffff0000, v17
	v_pk_mul_f32 v[30:31], v[30:31], v[32:33]
	s_nop 0
	v_cvt_pk_bf16_f32 v17, v30, v31
	global_store_dwordx2 v[14:15], v[16:17], off offset:96
	s_nop 0
	s_nop 0
	s_nop 0
	s_waitcnt vmcnt(23)
	v_mov_b32_e32 v16, v134
	v_mov_b32_e32 v17, v135
	v_mov_b32_e32 v30, v192
	v_mov_b32_e32 v31, v193
	v_mov_b32_e32 v32, v194
	v_mov_b32_e32 v33, v195
	v_pk_mul_f32 v[30:31], v[48:49], v[30:31]
	v_lshlrev_b32_e32 v48, 16, v16
	v_and_b32_e32 v49, 0xffff0000, v16
	v_pk_mul_f32 v[30:31], v[30:31], v[48:49]
	s_nop 0
	v_cvt_pk_bf16_f32 v16, v30, v31
	v_pk_mul_f32 v[30:31], v[46:47], v[6:7] op_sel_hi:[1,0]
	s_nop 0
	v_pk_mul_f32 v[30:31], v[30:31], v[32:33]
	v_lshlrev_b32_e32 v32, 16, v17
	v_and_b32_e32 v33, 0xffff0000, v17
	v_pk_mul_f32 v[30:31], v[30:31], v[32:33]
	s_nop 0
	v_cvt_pk_bf16_f32 v17, v30, v31
	global_store_dwordx2 v[14:15], v[16:17], off offset:112
	s_nop 0
	s_nop 0
	s_nop 0
	s_waitcnt vmcnt(22)
	v_mov_b32_e32 v16, v136
	v_mov_b32_e32 v17, v137
	v_mov_b32_e32 v30, v196
	v_mov_b32_e32 v31, v197
	v_mov_b32_e32 v32, v198
	v_mov_b32_e32 v33, v199
	v_pk_mul_f32 v[30:31], v[44:45], v[30:31]
	v_lshlrev_b32_e32 v44, 16, v16
	v_and_b32_e32 v45, 0xffff0000, v16
	v_pk_mul_f32 v[30:31], v[30:31], v[44:45]
	s_nop 0
	v_cvt_pk_bf16_f32 v16, v30, v31
	v_pk_mul_f32 v[30:31], v[42:43], v[6:7] op_sel_hi:[1,0]
	s_nop 0
	v_pk_mul_f32 v[30:31], v[30:31], v[32:33]
	v_lshlrev_b32_e32 v32, 16, v17
	v_and_b32_e32 v33, 0xffff0000, v17
	v_pk_mul_f32 v[30:31], v[30:31], v[32:33]
	s_nop 0
	v_cvt_pk_bf16_f32 v17, v30, v31
	global_store_dwordx2 v[14:15], v[16:17], off offset:128
	s_nop 0
	s_nop 0
	s_nop 0
	s_waitcnt vmcnt(21)
; __device__ __forceinline__ unsigned cvtpk(float lo, float hi) { f32x2 v = {lo, hi}; bf16x2_t b = __builtin_convertvector(v, bf16x2_t); return __builtin_bit_cast(unsigned, b); }
; __device__ __forceinline__ float bf_lo(unsigned u) { return __uint_as_float(u << 16); }
; __device__ __forceinline__ float bf_hi(unsigned u) { return __uint_as_float(u & 0xffff0000u); }
; template <bool DIFF>
; __device__ __forceinline__ void attn_unit(const AttnP& A, int b, int h, int qi, ldsp lds) {
;     ...
;             if (store_ok) {
; #pragma unroll
;                 for (int t = 0; t < NTD; ++t)
; #pragma unroll
;                     for (int g = 0; g < 4; ++g) {
;                         const int dv0 = 32 * t + 8 * g + 4 * hi;
;                         const u32x2 z = *(const u32x2*)(A.P + Rq * NP + zcol + dv0);
;                         const f32x4 sg = *(const f32x4*)(A.subg + h * 128 + dv0);
;                         u32x2 wv; wv.x = cvtpk(o[t][4 * g] * rn * sg[0] * bf_lo(z.x), o[t][4 * g + 1] * rn * sg[1] * bf_hi(z.x));
;                         wv.y = cvtpk(o[t][4 * g + 2] * rn * sg[2] * bf_lo(z.y), o[t][4 * g + 3] * rn * sg[3] * bf_hi(z.y));
;                         *(u32x2*)(mrow + mcol + dv0) = wv;
;                     }
	v_mov_b32_e32 v16, v138
	v_mov_b32_e32 v17, v139
	v_mov_b32_e32 v30, v228
	v_mov_b32_e32 v31, v229
	v_mov_b32_e32 v32, v230
	v_mov_b32_e32 v33, v231
	v_pk_mul_f32 v[30:31], v[40:41], v[30:31]
	v_lshlrev_b32_e32 v40, 16, v16
	v_and_b32_e32 v41, 0xffff0000, v16
	v_pk_mul_f32 v[30:31], v[30:31], v[40:41]
	s_nop 0
	v_cvt_pk_bf16_f32 v16, v30, v31
	v_pk_mul_f32 v[30:31], v[38:39], v[6:7] op_sel_hi:[1,0]
	s_nop 0
	v_pk_mul_f32 v[30:31], v[30:31], v[32:33]
	v_lshlrev_b32_e32 v32, 16, v17
	v_and_b32_e32 v33, 0xffff0000, v17
	v_pk_mul_f32 v[30:31], v[30:31], v[32:33]
	s_nop 0
	v_cvt_pk_bf16_f32 v17, v30, v31
	global_store_dwordx2 v[14:15], v[16:17], off offset:144
	s_nop 0
	s_nop 0
	s_nop 0
	s_waitcnt vmcnt(20)
	v_mov_b32_e32 v16, v140
	v_mov_b32_e32 v17, v141
	v_mov_b32_e32 v30, v232
	v_mov_b32_e32 v31, v233
	v_mov_b32_e32 v32, v234
	v_mov_b32_e32 v33, v235
	v_pk_mul_f32 v[30:31], v[36:37], v[30:31]
	v_lshlrev_b32_e32 v36, 16, v16
	v_and_b32_e32 v37, 0xffff0000, v16
	v_pk_mul_f32 v[30:31], v[30:31], v[36:37]
	s_nop 0
	v_cvt_pk_bf16_f32 v16, v30, v31
	v_pk_mul_f32 v[30:31], v[34:35], v[6:7] op_sel_hi:[1,0]
	s_nop 0
	v_pk_mul_f32 v[30:31], v[30:31], v[32:33]
	v_lshlrev_b32_e32 v32, 16, v17
	v_and_b32_e32 v33, 0xffff0000, v17
	v_pk_mul_f32 v[30:31], v[30:31], v[32:33]
	s_nop 0
	v_cvt_pk_bf16_f32 v17, v30, v31
	global_store_dwordx2 v[14:15], v[16:17], off offset:160
	s_nop 0
	s_nop 0
	s_nop 0
	s_waitcnt vmcnt(19)
	v_mov_b32_e32 v16, v142
	v_mov_b32_e32 v17, v143
	v_mov_b32_e32 v30, v236
	v_mov_b32_e32 v31, v237
	v_mov_b32_e32 v32, v238
	v_mov_b32_e32 v33, v239
	v_pk_mul_f32 v[28:29], v[28:29], v[30:31]
	v_lshlrev_b32_e32 v30, 16, v16
	v_and_b32_e32 v31, 0xffff0000, v16
	v_pk_mul_f32 v[28:29], v[28:29], v[30:31]
	v_pk_mul_f32 v[26:27], v[26:27], v[32:33]
	v_cvt_pk_bf16_f32 v16, v28, v29
	v_lshlrev_b32_e32 v28, 16, v17
	v_and_b32_e32 v29, 0xffff0000, v17
	v_pk_mul_f32 v[26:27], v[26:27], v[28:29]
	s_nop 0
	v_cvt_pk_bf16_f32 v17, v26, v27
	global_store_dwordx2 v[14:15], v[16:17], off offset:176
	s_nop 0
	s_nop 0
	s_nop 0
	s_waitcnt vmcnt(18)
	v_mov_b32_e32 v16, v144
	v_mov_b32_e32 v17, v145
	v_mov_b32_e32 v26, v240
	v_mov_b32_e32 v27, v241
	v_mov_b32_e32 v28, v242
	v_mov_b32_e32 v29, v243
	v_pk_mul_f32 v[24:25], v[24:25], v[26:27]
	v_lshlrev_b32_e32 v26, 16, v16
	v_and_b32_e32 v27, 0xffff0000, v16
	v_pk_mul_f32 v[24:25], v[24:25], v[26:27]
	v_pk_mul_f32 v[22:23], v[22:23], v[28:29]
	v_cvt_pk_bf16_f32 v16, v24, v25
	v_lshlrev_b32_e32 v24, 16, v17
	v_and_b32_e32 v25, 0xffff0000, v17
	v_pk_mul_f32 v[22:23], v[22:23], v[24:25]
	s_nop 0
	v_cvt_pk_bf16_f32 v17, v22, v23
	global_store_dwordx2 v[14:15], v[16:17], off offset:192
	s_nop 0
	s_nop 0
	s_nop 0
	s_waitcnt vmcnt(17)
	v_mov_b32_e32 v16, v146
	v_mov_b32_e32 v17, v147
	v_mov_b32_e32 v22, v244
	v_mov_b32_e32 v23, v245
	v_mov_b32_e32 v24, v246
	v_mov_b32_e32 v25, v247
	v_pk_mul_f32 v[20:21], v[20:21], v[22:23]
	v_lshlrev_b32_e32 v22, 16, v16
	v_and_b32_e32 v23, 0xffff0000, v16
	v_pk_mul_f32 v[20:21], v[20:21], v[22:23]
	v_pk_mul_f32 v[18:19], v[18:19], v[24:25]
	v_cvt_pk_bf16_f32 v16, v20, v21
	v_lshlrev_b32_e32 v20, 16, v17
	v_and_b32_e32 v21, 0xffff0000, v17
	v_pk_mul_f32 v[18:19], v[18:19], v[20:21]
	s_nop 0
	v_cvt_pk_bf16_f32 v17, v18, v19
	global_store_dwordx2 v[14:15], v[16:17], off offset:208
	s_nop 0
	s_nop 0
	s_nop 0
	s_waitcnt vmcnt(16)
	v_mov_b32_e32 v20, v164
	v_mov_b32_e32 v21, v165
	v_mov_b32_e32 v16, v248
	v_mov_b32_e32 v17, v249
	v_mov_b32_e32 v18, v250
	v_mov_b32_e32 v19, v251
	v_pk_mul_f32 v[10:11], v[10:11], v[16:17]
	v_lshlrev_b32_e32 v16, 16, v20
	v_and_b32_e32 v17, 0xffff0000, v20
	v_pk_mul_f32 v[10:11], v[10:11], v[16:17]
	v_pk_mul_f32 v[8:9], v[8:9], v[18:19]
	v_lshlrev_b32_e32 v16, 16, v21
	v_and_b32_e32 v17, 0xffff0000, v21
	v_pk_mul_f32 v[8:9], v[8:9], v[16:17]
	v_cvt_pk_bf16_f32 v10, v10, v11
	v_cvt_pk_bf16_f32 v11, v8, v9
	global_store_dwordx2 v[14:15], v[10:11], off offset:224
	s_nop 0
	s_nop 0
	s_nop 0
	s_waitcnt vmcnt(15)
	v_mov_b32_e32 v12, v204
	v_mov_b32_e32 v13, v205
	v_mov_b32_e32 v8, v120
	v_mov_b32_e32 v9, v121
	v_mov_b32_e32 v10, v122
	v_mov_b32_e32 v11, v123
	v_lshlrev_b32_e32 v6, 16, v13
	s_nop 0
	v_pk_mul_f32 v[4:5], v[4:5], v[8:9]
	v_lshlrev_b32_e32 v8, 16, v12
	v_and_b32_e32 v9, 0xffff0000, v12
	v_pk_mul_f32 v[2:3], v[2:3], v[10:11]
	v_and_b32_e32 v7, 0xffff0000, v13
	v_pk_mul_f32 v[4:5], v[4:5], v[8:9]
	v_pk_mul_f32 v[2:3], v[2:3], v[6:7]
	v_cvt_pk_bf16_f32 v4, v4, v5
	v_cvt_pk_bf16_f32 v5, v2, v3
	global_store_dwordx2 v[14:15], v[4:5], off offset:240
	s_branch .LBB0_437
